# w_out split-K 4->8 slices, q/k gain loads hoisted out of the 8 row groups in the w_in epilogue
# speedup vs baseline: 1.0396x; 1.0101x over previous
; template <class T> __device__ __forceinline__ T* kptr(int i) { return (T*)(__attribute__((address_space(1))) T*)karg(i); }
;     __device__ __forceinline__ void operator()(const f32x4 (&acc)[2][2][4][2], const Unit& u, int wr, int wc, int fr, int fq) const {
;     ...
;                         float ss = 0.f;
; #pragma unroll
;                         for (int bj = 0; bj < 2; ++bj)
; #pragma unroll
;                             for (int n = 0; n < 2; ++n) { const f32x4 x = v[bj][n]; ss += (x[0] * x[0] + x[1] * x[1]) + (x[2] * x[2] + x[3] * x[3]); }
;                         ss += __shfl_xor(ss, 16); ss += __shfl_xor(ss, 32);
;                         const float rn = __builtin_amdgcn_rsqf(ss * (1.0f / HD) + EPS) * (kind == 0 ? QSCALE : 1.0f);
;                         const float* gg = (const float*)kptr<float>(kind == 0 ? 12 : 13) + l * HD;
; #pragma unroll
;                         for (int bj = 0; bj < 2; ++bj)
; #pragma unroll
;                             for (int n = 0; n < 2; ++n) v[bj][n] = v[bj][n] * rn * *(const f32x4*)(gg + 32 * bj + 16 * n + 4 * fq);
.LBB0_270:
	v_pk_mul_f32 v[146:147], v[130:131], v[130:131]
	v_pk_mul_f32 v[148:149], v[128:129], v[128:129]
	v_mul_f32_e32 v144, v136, v136
	v_pk_mov_b32 v[150:151], v[148:149], v[146:147] op_sel:[1,0]
	v_mov_b32_e32 v149, v147
	v_pk_add_f32 v[146:147], v[150:151], v[148:149]
	v_pk_mul_f32 v[148:149], v[134:135], v[134:135]
	v_pk_mul_f32 v[150:151], v[132:133], v[132:133]
	v_pk_add_f32 v[146:147], v[146:147], v[146:147] op_sel_hi:[0,1]
	v_pk_mov_b32 v[156:157], v[150:151], v[148:149] op_sel:[1,0]
	v_mov_b32_e32 v151, v149
	v_pk_add_f32 v[148:149], v[156:157], v[150:151]
	v_pk_fma_f32 v[150:151], v[136:137], v[136:137], v[144:145] op_sel_hi:[1,1,0]
	v_mul_f32_e32 v144, v138, v138
	v_pk_add_f32 v[148:149], v[148:149], v[148:149] op_sel_hi:[0,1]
	v_pk_fma_f32 v[156:157], v[138:139], v[138:139], v[144:145] op_sel_hi:[1,1,0]
	v_mul_f32_e32 v150, v140, v140
	v_mul_f32_e32 v156, v141, v141
	v_mul_f32_e32 v146, v142, v142
	v_mul_f32_e32 v148, v143, v143
	v_pk_add_f32 v[150:151], v[150:151], v[156:157]
	v_pk_add_f32 v[146:147], v[146:147], v[148:149]
	s_load_dwordx2 s[42:43], s[14:15], 0x0
	v_pk_add_f32 v[146:147], v[150:151], v[146:147]
	s_lshl_b64 s[54:55], s[4:5], 2
	v_add_f32_e32 v144, v146, v147
	v_and_b32_e32 v147, 64, v191
	v_xor_b32_e32 v146, 16, v191
	v_add_u32_e32 v147, 64, v147
	v_cmp_lt_i32_e32 vcc, v146, v147
	s_waitcnt lgkmcnt(0)
	s_add_u32 s42, s42, s54
	s_addc_u32 s43, s43, s55
	v_cndmask_b32_e32 v146, v191, v146, vcc
	v_lshlrev_b32_e32 v146, 2, v146
	ds_bpermute_b32 v146, v146, v144
	v_lshlrev_b32_e32 v150, 2, v174
	s_waitcnt lgkmcnt(0)
	v_add_f32_e32 v144, v144, v146
	v_xor_b32_e32 v146, 32, v191
	v_cmp_lt_i32_e32 vcc, v146, v147
	s_nop 1
	v_cndmask_b32_e32 v146, v191, v146, vcc
	v_lshlrev_b32_e32 v146, 2, v146
	ds_bpermute_b32 v146, v146, v144
	s_waitcnt lgkmcnt(0)
	v_add_f32_e32 v144, v144, v146
	v_fmamk_f32 v144, v144, 0x3c800000, v175
	v_rsq_f32_e32 v144, v144
	s_nop 0
	v_mul_f32_e32 v144, v214, v144
	v_pk_mul_f32 v[146:147], v[128:129], v[144:145] op_sel_hi:[1,0]
	v_pk_mul_f32 v[148:149], v[130:131], v[144:145] op_sel_hi:[1,0]
	global_load_dwordx4 v[228:231], v150, s[42:43]
	global_load_dwordx4 v[232:235], v150, s[42:43] offset:64
	global_load_dwordx4 v[236:239], v150, s[42:43] offset:128
	global_load_dwordx4 v[240:243], v150, s[42:43] offset:192
	s_waitcnt vmcnt(0)
	v_pk_mul_f32 v[130:131], v[230:231], v[148:149]
	v_pk_mul_f32 v[128:129], v[228:229], v[146:147]
	v_pk_mul_f32 v[146:147], v[132:133], v[144:145] op_sel_hi:[1,0]
	v_pk_mul_f32 v[148:149], v[134:135], v[144:145] op_sel_hi:[1,0]
	v_pk_mul_f32 v[134:135], v[234:235], v[148:149]
	v_pk_mul_f32 v[132:133], v[232:233], v[146:147]
	v_pk_mul_f32 v[146:147], v[136:137], v[144:145] op_sel_hi:[1,0]
	v_pk_mul_f32 v[148:149], v[138:139], v[144:145] op_sel_hi:[1,0]
	v_pk_mul_f32 v[138:139], v[238:239], v[148:149]
	v_pk_mul_f32 v[136:137], v[236:237], v[146:147]
	v_pk_mul_f32 v[146:147], v[140:141], v[144:145] op_sel_hi:[1,0]
	v_pk_mul_f32 v[148:149], v[142:143], v[144:145] op_sel_hi:[1,0]
	v_pk_mul_f32 v[142:143], v[242:243], v[148:149]
	v_pk_mul_f32 v[140:141], v[240:241], v[146:147]
	s_mov_b64 s[42:43], -1
	s_and_b64 vcc, exec, s[96:97]
	s_cbranch_vccz .LBB0_173

; template <class T> __device__ __forceinline__ T* kptr(int i) { return (T*)(__attribute__((address_space(1))) T*)karg(i); }
;     __device__ __forceinline__ void operator()(const f32x4 (&acc)[2][2][4][2], const Unit& u, int wr, int wc, int fr, int fq) const {
;     ...
;                         float ss = 0.f;
; #pragma unroll
;                         for (int bj = 0; bj < 2; ++bj)
; #pragma unroll
;                             for (int n = 0; n < 2; ++n) { const f32x4 x = v[bj][n]; ss += (x[0] * x[0] + x[1] * x[1]) + (x[2] * x[2] + x[3] * x[3]); }
;                         ss += __shfl_xor(ss, 16); ss += __shfl_xor(ss, 32);
;                         const float rn = __builtin_amdgcn_rsqf(ss * (1.0f / HD) + EPS) * (kind == 0 ? QSCALE : 1.0f);
;                         const float* gg = (const float*)kptr<float>(kind == 0 ? 12 : 13) + l * HD;
; #pragma unroll
;                         for (int bj = 0; bj < 2; ++bj)
; #pragma unroll
;                             for (int n = 0; n < 2; ++n) v[bj][n] = v[bj][n] * rn * *(const f32x4*)(gg + 32 * bj + 16 * n + 4 * fq);
.LBB0_280:
	v_pk_mul_f32 v[146:147], v[130:131], v[130:131]
	v_pk_mul_f32 v[148:149], v[128:129], v[128:129]
	v_mul_f32_e32 v144, v136, v136
	v_pk_mov_b32 v[150:151], v[148:149], v[146:147] op_sel:[1,0]
	v_mov_b32_e32 v149, v147
	v_pk_add_f32 v[146:147], v[150:151], v[148:149]
	v_pk_mul_f32 v[148:149], v[134:135], v[134:135]
	v_pk_mul_f32 v[150:151], v[132:133], v[132:133]
	v_pk_add_f32 v[146:147], v[146:147], v[146:147] op_sel_hi:[0,1]
	v_pk_mov_b32 v[156:157], v[150:151], v[148:149] op_sel:[1,0]
	v_mov_b32_e32 v151, v149
	v_pk_add_f32 v[148:149], v[156:157], v[150:151]
	v_pk_fma_f32 v[150:151], v[136:137], v[136:137], v[144:145] op_sel_hi:[1,1,0]
	v_mul_f32_e32 v144, v138, v138
	v_pk_add_f32 v[148:149], v[148:149], v[148:149] op_sel_hi:[0,1]
	v_pk_fma_f32 v[156:157], v[138:139], v[138:139], v[144:145] op_sel_hi:[1,1,0]
	v_mul_f32_e32 v150, v140, v140
	v_mul_f32_e32 v156, v141, v141
	v_mul_f32_e32 v146, v142, v142
	v_mul_f32_e32 v148, v143, v143
	v_pk_add_f32 v[150:151], v[150:151], v[156:157]
	v_pk_add_f32 v[146:147], v[146:147], v[148:149]
	v_pk_add_f32 v[146:147], v[150:151], v[146:147]
	s_lshl_b64 s[54:55], s[4:5], 2
	v_add_f32_e32 v144, v146, v147
	v_and_b32_e32 v147, 64, v191
	v_xor_b32_e32 v146, 16, v191
	v_add_u32_e32 v147, 64, v147
	v_cmp_lt_i32_e32 vcc, v146, v147
	s_waitcnt lgkmcnt(0)
	v_cndmask_b32_e32 v146, v191, v146, vcc
	v_lshlrev_b32_e32 v146, 2, v146
	ds_bpermute_b32 v146, v146, v144
	v_lshlrev_b32_e32 v150, 2, v174
	s_waitcnt lgkmcnt(0)
	v_add_f32_e32 v144, v144, v146
	v_xor_b32_e32 v146, 32, v191
	v_cmp_lt_i32_e32 vcc, v146, v147
	s_nop 1
	v_cndmask_b32_e32 v146, v191, v146, vcc
	v_lshlrev_b32_e32 v146, 2, v146
	ds_bpermute_b32 v146, v146, v144
	s_waitcnt lgkmcnt(0)
	v_add_f32_e32 v144, v144, v146
	v_fmamk_f32 v144, v144, 0x3c800000, v175
	v_rsq_f32_e32 v144, v144
	s_nop 0
	v_mul_f32_e32 v144, v214, v144
	v_pk_mul_f32 v[146:147], v[128:129], v[144:145] op_sel_hi:[1,0]
	v_pk_mul_f32 v[148:149], v[130:131], v[144:145] op_sel_hi:[1,0]
	v_pk_mul_f32 v[130:131], v[230:231], v[148:149]
	v_pk_mul_f32 v[128:129], v[228:229], v[146:147]
	v_pk_mul_f32 v[146:147], v[132:133], v[144:145] op_sel_hi:[1,0]
	v_pk_mul_f32 v[148:149], v[134:135], v[144:145] op_sel_hi:[1,0]
	v_pk_mul_f32 v[134:135], v[234:235], v[148:149]
	v_pk_mul_f32 v[132:133], v[232:233], v[146:147]
	v_pk_mul_f32 v[146:147], v[136:137], v[144:145] op_sel_hi:[1,0]
	v_pk_mul_f32 v[148:149], v[138:139], v[144:145] op_sel_hi:[1,0]
	v_pk_mul_f32 v[138:139], v[238:239], v[148:149]
	v_pk_mul_f32 v[136:137], v[236:237], v[146:147]
	v_pk_mul_f32 v[146:147], v[140:141], v[144:145] op_sel_hi:[1,0]
	v_pk_mul_f32 v[148:149], v[142:143], v[144:145] op_sel_hi:[1,0]
	v_pk_mul_f32 v[142:143], v[242:243], v[148:149]
	v_pk_mul_f32 v[140:141], v[240:241], v[146:147]
	s_andn2_b64 vcc, exec, s[96:97]
	s_mov_b64 s[2:3], -1
	s_cbranch_vccnz .LBB0_185

; template <class T> __device__ __forceinline__ T* kptr(int i) { return (T*)(__attribute__((address_space(1))) T*)karg(i); }
;     __device__ __forceinline__ void operator()(const f32x4 (&acc)[2][2][4][2], const Unit& u, int wr, int wc, int fr, int fq) const {
;     ...
;                         float ss = 0.f;
; #pragma unroll
;                         for (int bj = 0; bj < 2; ++bj)
; #pragma unroll
;                             for (int n = 0; n < 2; ++n) { const f32x4 x = v[bj][n]; ss += (x[0] * x[0] + x[1] * x[1]) + (x[2] * x[2] + x[3] * x[3]); }
;                         ss += __shfl_xor(ss, 16); ss += __shfl_xor(ss, 32);
;                         const float rn = __builtin_amdgcn_rsqf(ss * (1.0f / HD) + EPS) * (kind == 0 ? QSCALE : 1.0f);
;                         const float* gg = (const float*)kptr<float>(kind == 0 ? 12 : 13) + l * HD;
; #pragma unroll
;                         for (int bj = 0; bj < 2; ++bj)
; #pragma unroll
;                             for (int n = 0; n < 2; ++n) v[bj][n] = v[bj][n] * rn * *(const f32x4*)(gg + 32 * bj + 16 * n + 4 * fq);
.LBB0_340:
	v_pk_mul_f32 v[146:147], v[130:131], v[130:131]
	v_pk_mul_f32 v[148:149], v[128:129], v[128:129]
	v_mul_f32_e32 v144, v136, v136
	v_pk_mov_b32 v[150:151], v[148:149], v[146:147] op_sel:[1,0]
	v_mov_b32_e32 v149, v147
	v_pk_add_f32 v[146:147], v[150:151], v[148:149]
	v_pk_mul_f32 v[148:149], v[134:135], v[134:135]
	v_pk_mul_f32 v[150:151], v[132:133], v[132:133]
	v_pk_add_f32 v[146:147], v[146:147], v[146:147] op_sel_hi:[0,1]
	v_pk_mov_b32 v[156:157], v[150:151], v[148:149] op_sel:[1,0]
	v_mov_b32_e32 v151, v149
	v_pk_add_f32 v[148:149], v[156:157], v[150:151]
	v_pk_fma_f32 v[150:151], v[136:137], v[136:137], v[144:145] op_sel_hi:[1,1,0]
	v_mul_f32_e32 v144, v138, v138
	v_pk_add_f32 v[148:149], v[148:149], v[148:149] op_sel_hi:[0,1]
	v_pk_fma_f32 v[156:157], v[138:139], v[138:139], v[144:145] op_sel_hi:[1,1,0]
	v_mul_f32_e32 v150, v140, v140
	v_mul_f32_e32 v156, v141, v141
	v_mul_f32_e32 v146, v142, v142
	v_mul_f32_e32 v148, v143, v143
	v_pk_add_f32 v[150:151], v[150:151], v[156:157]
	v_pk_add_f32 v[146:147], v[146:147], v[148:149]
	v_pk_add_f32 v[146:147], v[150:151], v[146:147]
	s_lshl_b64 s[14:15], s[4:5], 2
	v_add_f32_e32 v144, v146, v147
	v_and_b32_e32 v147, 64, v191
	v_xor_b32_e32 v146, 16, v191
	v_add_u32_e32 v147, 64, v147
	v_cmp_lt_i32_e32 vcc, v146, v147
	s_waitcnt lgkmcnt(0)
	s_add_u32 s2, s2, s14
	s_addc_u32 s3, s3, s15
	v_cndmask_b32_e32 v146, v191, v146, vcc
	v_lshlrev_b32_e32 v146, 2, v146
	ds_bpermute_b32 v146, v146, v144
	v_lshlrev_b32_e32 v150, 2, v174
	s_waitcnt lgkmcnt(0)
	v_add_f32_e32 v144, v144, v146
	v_xor_b32_e32 v146, 32, v191
	v_cmp_lt_i32_e32 vcc, v146, v147
	s_nop 1
	v_cndmask_b32_e32 v146, v191, v146, vcc
	v_lshlrev_b32_e32 v146, 2, v146
	ds_bpermute_b32 v146, v146, v144
	s_waitcnt lgkmcnt(0)
	v_add_f32_e32 v144, v144, v146
	v_fmamk_f32 v144, v144, 0x3c800000, v175
	v_rsq_f32_e32 v144, v144
	s_nop 0
	v_mul_f32_e32 v144, v214, v144
	v_pk_mul_f32 v[146:147], v[128:129], v[144:145] op_sel_hi:[1,0]
	v_pk_mul_f32 v[148:149], v[130:131], v[144:145] op_sel_hi:[1,0]
	v_pk_mul_f32 v[130:131], v[230:231], v[148:149]
	v_pk_mul_f32 v[128:129], v[228:229], v[146:147]
	v_pk_mul_f32 v[146:147], v[132:133], v[144:145] op_sel_hi:[1,0]
	v_pk_mul_f32 v[148:149], v[134:135], v[144:145] op_sel_hi:[1,0]
	v_pk_mul_f32 v[134:135], v[234:235], v[148:149]
	v_pk_mul_f32 v[132:133], v[232:233], v[146:147]
	v_pk_mul_f32 v[146:147], v[136:137], v[144:145] op_sel_hi:[1,0]
	v_pk_mul_f32 v[148:149], v[138:139], v[144:145] op_sel_hi:[1,0]
	v_pk_mul_f32 v[138:139], v[238:239], v[148:149]
	v_pk_mul_f32 v[136:137], v[236:237], v[146:147]
	v_pk_mul_f32 v[146:147], v[140:141], v[144:145] op_sel_hi:[1,0]
	v_pk_mul_f32 v[148:149], v[142:143], v[144:145] op_sel_hi:[1,0]
	v_pk_mul_f32 v[142:143], v[242:243], v[148:149]
	v_pk_mul_f32 v[140:141], v[240:241], v[146:147]
	s_andn2_b64 vcc, exec, s[96:97]
	s_mov_b64 s[2:3], -1
	s_cbranch_vccnz .LBB0_257

;     __host__ __device__ bool next(int i, Unit& u) const {
;         const long L = (long)i * G + c; if (L >= nwg + nsp) return false;
;         if (L >= nwg) { const int Ls = (int)L - nwg, t = Ls / S, sl = Ls % S; u.pk = mark ? -2 : sl; u.pn = pn0 + t % nNs; u.pm = pm0 + t / nNs; u.kofs = sl * nts * BK; u.nt = nts; return true; }
;         int wgid = (int)L; { const int q = nwg / NXCD, r = nwg % NXCD, xcd = wgid % NXCD, off = wgid / NXCD; wgid = (xcd < r ? xcd * (q + 1) : r * (q + 1) + (xcd - r) * q) + off; }
;         const int nig = WGM * nN, gid = wgid / nig, fm = gid * WGM, gsz = (nM - fm) < WGM ? (nM - fm) : WGM;
;         u.pm = fm + ((wgid % nig) % gsz); u.pn = (wgid % nig) / gsz; u.pk = -1; u.kofs = 0; u.nt = nt; return true;
.LBB0_534:
	s_andn2_b64 vcc, exec, s[2:3]
	s_cbranch_vccnz .LBB0_646
	s_add_u32 s2, s0, s92
	s_mov_b32 s10, s76
	s_addc_u32 s3, s1, s93
	s_waitcnt lgkmcnt(0)
	s_load_dwordx2 s[34:35], s[0:1], 0x98
	s_load_dwordx2 s[14:15], s[2:3], 0x0
	s_load_dwordx2 s[22:23], s[0:1], 0x90
	v_mov_b32_e32 v8, v173
	s_cmp_lt_u32 s10, 0x40
	s_cselect_b32 s24, 0x100, 0
	s_cmp_lt_u32 s10, 0x100
	s_cselect_b32 s88, 0, 0x100
	s_cmp_lt_u32 s10, 0x140
	s_cselect_b32 s88, s88, 0
	s_add_u32 s10, s10, s24
	s_sub_u32 s10, s10, s88
	s_cmpk_lt_i32 s10, 0x140
	s_cselect_b64 s[26:27], -1, 0
	s_cmpk_gt_i32 s10, 0x13f
	v_readfirstlane_b32 s36, v8
	s_cbranch_scc1 .LBB0_544
	s_cmpk_lt_i32 s10, 0x100
	s_mov_b64 s[28:29], -1
	s_cbranch_scc1 .LBB0_538
	s_bfe_u32 s11, s10, 0x30003
	s_and_b32 s4, s10, 7
	v_sub_co_u32_e64 v0, s[2:3], s11, 4
	s_and_b64 s[2:3], s[2:3], exec
	v_readfirstlane_b32 s2, v0
	s_cselect_b32 s88, s11, s2
	s_cmp_gt_u32 s11, 3
	s_cselect_b32 s24, 0x41, 64
	s_lshl_b32 s2, s4, 7
	s_mov_b64 s[28:29], 0
.LBB0_538:
	s_andn2_b64 vcc, exec, s[28:29]
	s_mov_b32 s69, 2
	s_cbranch_vccnz .LBB0_544
	s_ashr_i32 s2, s10, 31
	s_lshr_b32 s2, s2, 29
	s_add_i32 s4, s10, s2
	s_and_b32 s2, s4, -8
	s_sub_i32 s11, s10, s2
	s_cmp_gt_i32 s11, -1
	s_mov_b64 s[2:3], -1
	s_cbranch_scc0 .LBB0_541
	s_lshl_b32 s18, s11, 5
	s_mov_b64 s[2:3], 0

;     __host__ __device__ bool next(int i, Unit& u) const {
;         const long L = (long)i * G + c; if (L >= nwg + nsp) return false;
;         if (L >= nwg) { const int Ls = (int)L - nwg, t = Ls / S, sl = Ls % S; u.pk = mark ? -2 : sl; u.pn = pn0 + t % nNs; u.pm = pm0 + t / nNs; u.kofs = sl * nts * BK; u.nt = nts; return true; }
;         int wgid = (int)L; { const int q = nwg / NXCD, r = nwg % NXCD, xcd = wgid % NXCD, off = wgid / NXCD; wgid = (xcd < r ? xcd * (q + 1) : r * (q + 1) + (xcd - r) * q) + off; }
;         const int nig = WGM * nN, gid = wgid / nig, fm = gid * WGM, gsz = (nM - fm) < WGM ? (nM - fm) : WGM;
;         u.pm = fm + ((wgid % nig) % gsz); u.pn = (wgid % nig) / gsz; u.pk = -1; u.kofs = 0; u.nt = nt; return true;
.LBB0_550:
	s_mov_b32 s10, s76
	s_add_i32 s65, s65, 1
	s_mul_i32 s37, s65, s48
	s_mul_hi_u32 s40, s65, s33
	s_add_i32 s37, s40, s37
	s_mul_i32 s40, s65, s33
	s_add_u32 s40, s40, s10
	s_addc_u32 s41, s37, s66
	s_cmp_lt_u32 s40, 0x140
	s_cselect_b64 s[42:43], -1, 0
	s_cmp_gt_u32 s40, 0x13f
	s_cselect_b64 vcc, -1, 0
	s_cbranch_vccnz .LBB0_559
	s_cmp_lt_u32 s40, 0x40
	s_cselect_b32 s36, 0x100, 0
	s_cmp_lt_u32 s40, 0x100
	s_cselect_b32 s37, 0, 0x100
	s_cmp_lt_u32 s40, 0x140
	s_cselect_b32 s37, s37, 0
	s_add_u32 s40, s40, s36
	s_sub_u32 s40, s40, s37
	v_cmp_lt_i64_e32 vcc, s[40:41], v[162:163]
	s_mov_b64 s[50:51], -1
	s_and_b64 vcc, exec, vcc
	s_cbranch_vccnz .LBB0_553
	s_add_i32 s36, s40, 0xffffff00
	s_and_b32 s67, s36, 7
	s_lshr_b32 s44, s36, 3
	s_lshr_b32 s46, s36, 5
	s_and_b32 s44, s44, 3
	s_add_i32 s46, s46, 64
	s_lshl_b32 s36, s67, 7
	s_mov_b64 s[50:51], 0
.LBB0_553:
	s_andn2_b64 vcc, exec, s[50:51]
	s_mov_b32 s68, 2
	s_cbranch_vccnz .LBB0_559
	s_ashr_i32 s36, s40, 31
	s_lshr_b32 s36, s36, 29
	s_add_i32 s41, s40, s36
	s_and_b32 s36, s41, -8
	s_sub_i32 s40, s40, s36
	s_cmp_gt_i32 s40, -1
	s_mov_b64 s[36:37], -1
	s_cbranch_scc0 .LBB0_556
	s_lshl_b32 s44, s40, 5
	s_mov_b64 s[36:37], 0

; #define OPQ_TID() int tid = threadIdx.x; asm volatile("" : "+v"(tid)); const int lane = tid & 63, wave = __builtin_amdgcn_readfirstlane(tid >> 6), gw = blockIdx.x * NWAVES + wave; (void)lane; (void)gw
; #define KIN(i) ((const float*)kptr<float>(i))
; __device__ __forceinline__ void sample_combine(const float* XinS  , float* X, const float* slab, int S, bf16_t* XB, float* rss, int gw, int NGW, int lane) {
;     for (int r = gw; r < TS; r += NGW) { const size_t row = (size_t)TP + r; float ss = 0.f;
; #pragma unroll
;         for (int j = 0; j < 4; ++j) { const int c = 4 * lane + 256 * j; f32x4 v = *(const f32x4*)(XinS + (size_t)r * DM + c);
; __global__ void __launch_bounds__(NWAVES * 64, 2) fwd_mega(Args args) {
;     ...
;         if (IN(pb + 3) && EN_P4) {
;             OPQ_TID();
;             unsigned char* ws = KWS;
;             sample_combine(l == 0 ? KIN(1) : (const float*)KOUT + (size_t)TP * DM, KOUT, (const float*)(ws + WS_Q), SPLIT4, (bf16_t*)(ws + WS_XB), (float*)(ws + WS_RSS) + (size_t)(2 * l + 1) * MT, gw, NGW, lane);
.LBB0_653:
	s_load_dwordx2 s[22:23], s[0:1], 0x90
	s_ashr_i32 s4, s4, 6
	s_mul_i32 s4, s4, s33
	s_add_i32 s14, s4, s76
	s_cmpk_gt_i32 s14, 0x1ff
	s_cbranch_scc1 .LBB0_659
	v_and_b32_e32 v1, 64, v191
	v_add_u32_e32 v1, 64, v1
	v_xor_b32_e32 v2, 1, v191
	v_cmp_lt_i32_e32 vcc, v2, v1
	s_ashr_i32 s15, s14, 31
	s_lshl_b64 s[10:11], s[14:15], 12
	v_cndmask_b32_e32 v2, v191, v2, vcc
	v_lshlrev_b32_e32 v16, 2, v2
	v_xor_b32_e32 v2, 2, v191
	v_cmp_lt_i32_e32 vcc, v2, v1
	s_waitcnt lgkmcnt(0)
	s_add_u32 s22, s22, s10
	s_addc_u32 s23, s23, s11
	v_cndmask_b32_e32 v2, v191, v2, vcc
	v_lshlrev_b32_e32 v17, 2, v2
	v_xor_b32_e32 v2, 4, v191
	v_cmp_lt_i32_e32 vcc, v2, v1
	s_add_u32 s24, s24, s10
	s_addc_u32 s25, s25, s11
	v_cndmask_b32_e32 v2, v191, v2, vcc
	v_lshlrev_b32_e32 v18, 2, v2
	v_xor_b32_e32 v2, 8, v191
	v_cmp_lt_i32_e32 vcc, v2, v1
	s_add_u32 s26, s2, s10
	s_addc_u32 s27, s3, s11
	v_cndmask_b32_e32 v2, v191, v2, vcc
	v_lshlrev_b32_e32 v19, 2, v2
	v_xor_b32_e32 v2, 16, v191
	v_cmp_lt_i32_e32 vcc, v2, v1
	s_mul_i32 s18, s62, 0x21000
	s_lshl_b64 s[10:11], s[14:15], 2
	v_cndmask_b32_e32 v2, v191, v2, vcc
	s_mul_hi_u32 s4, s62, 0x21000
	s_add_u32 s10, s18, s10
	v_lshlrev_b32_e32 v20, 2, v2
	v_xor_b32_e32 v2, 32, v191
	s_addc_u32 s11, s4, s11
	v_cmp_lt_i32_e32 vcc, v2, v1
	s_add_u32 s4, s10, 0x5520800
	v_and_b32_e32 v0, 63, v0
	v_cndmask_b32_e32 v1, v191, v2, vcc
	s_addc_u32 s10, s11, 0
	s_lshl_b64 s[18:19], s[14:15], 11
	v_cmp_eq_u32_e64 s[38:39], 0, v0
	v_lshlrev_b32_e32 v21, 2, v1
	v_lshlrev_b32_e32 v152, 4, v0
	v_lshl_or_b32 v0, v0, 3, s18
	v_mov_b32_e32 v1, s19
	s_branch .LBB0_656

; __device__ __forceinline__ void sample_combine(const float* XinS  , float* X, const float* slab, int S, bf16_t* XB, float* rss, int gw, int NGW, int lane) {
;     for (int r = gw; r < TS; r += NGW) { const size_t row = (size_t)TP + r; float ss = 0.f;
; #pragma unroll
;         for (int j = 0; j < 4; ++j) { const int c = 4 * lane + 256 * j; f32x4 v = *(const f32x4*)(XinS + (size_t)r * DM + c);
;             for (int s = 0; s < S; ++s) v += *(const f32x4*)(slab + ((size_t)s * TS + r) * DM + c);
;             *(f32x4*)(X + row * DM + c) = v; ss += (v[0] * v[0] + v[1] * v[1]) + (v[2] * v[2] + v[3] * v[3]);
.LBB0_656:
	s_waitcnt lgkmcnt(0)
	global_load_dwordx4 v[32:35], v152, s[24:25]
	global_load_dwordx4 v[36:39], v152, s[24:25] offset:1024
	global_load_dwordx4 v[40:43], v152, s[24:25] offset:2048
	global_load_dwordx4 v[44:47], v152, s[24:25] offset:3072
	s_add_u32 s18, s26, 0x7b00000
	s_addc_u32 s19, s27, 0
	global_load_dwordx4 v[48:51], v152, s[18:19]
	global_load_dwordx4 v[52:55], v152, s[18:19] offset:1024
	global_load_dwordx4 v[56:59], v152, s[18:19] offset:2048
	global_load_dwordx4 v[60:63], v152, s[18:19] offset:3072
	s_add_u32 s18, s18, 0x200000
	s_addc_u32 s19, s19, 0
	global_load_dwordx4 v[64:67], v152, s[18:19]
	global_load_dwordx4 v[68:71], v152, s[18:19] offset:1024
	global_load_dwordx4 v[72:75], v152, s[18:19] offset:2048
	global_load_dwordx4 v[76:79], v152, s[18:19] offset:3072
	s_add_u32 s18, s18, 0x200000
	s_addc_u32 s19, s19, 0
	global_load_dwordx4 v[80:83], v152, s[18:19]
	global_load_dwordx4 v[84:87], v152, s[18:19] offset:1024
	global_load_dwordx4 v[88:91], v152, s[18:19] offset:2048
	global_load_dwordx4 v[92:95], v152, s[18:19] offset:3072
	s_add_u32 s18, s18, 0x200000
	s_addc_u32 s19, s19, 0
	global_load_dwordx4 v[96:99], v152, s[18:19]
	global_load_dwordx4 v[100:103], v152, s[18:19] offset:1024
	global_load_dwordx4 v[104:107], v152, s[18:19] offset:2048
	global_load_dwordx4 v[108:111], v152, s[18:19] offset:3072
	s_add_u32 s18, s18, 0x200000
	s_addc_u32 s19, s19, 0
	s_waitcnt vmcnt(0)
	v_pk_add_f32 v[32:33], v[32:33], v[48:49]
	v_pk_add_f32 v[34:35], v[34:35], v[50:51]
	v_pk_add_f32 v[36:37], v[36:37], v[52:53]
	v_pk_add_f32 v[38:39], v[38:39], v[54:55]
	v_pk_add_f32 v[40:41], v[40:41], v[56:57]
	v_pk_add_f32 v[42:43], v[42:43], v[58:59]
	v_pk_add_f32 v[44:45], v[44:45], v[60:61]
	v_pk_add_f32 v[46:47], v[46:47], v[62:63]
	v_pk_add_f32 v[32:33], v[32:33], v[64:65]
	v_pk_add_f32 v[34:35], v[34:35], v[66:67]
	v_pk_add_f32 v[36:37], v[36:37], v[68:69]
	v_pk_add_f32 v[38:39], v[38:39], v[70:71]
	v_pk_add_f32 v[40:41], v[40:41], v[72:73]
	v_pk_add_f32 v[42:43], v[42:43], v[74:75]
	v_pk_add_f32 v[44:45], v[44:45], v[76:77]
	v_pk_add_f32 v[46:47], v[46:47], v[78:79]
	v_pk_add_f32 v[32:33], v[32:33], v[80:81]
	v_pk_add_f32 v[34:35], v[34:35], v[82:83]
	v_pk_add_f32 v[36:37], v[36:37], v[84:85]
	v_pk_add_f32 v[38:39], v[38:39], v[86:87]
	v_pk_add_f32 v[40:41], v[40:41], v[88:89]
	v_pk_add_f32 v[42:43], v[42:43], v[90:91]
	v_pk_add_f32 v[44:45], v[44:45], v[92:93]
	v_pk_add_f32 v[46:47], v[46:47], v[94:95]
	v_pk_add_f32 v[32:33], v[32:33], v[96:97]
	v_pk_add_f32 v[34:35], v[34:35], v[98:99]
	v_pk_add_f32 v[36:37], v[36:37], v[100:101]
	v_pk_add_f32 v[38:39], v[38:39], v[102:103]
	v_pk_add_f32 v[40:41], v[40:41], v[104:105]
	v_pk_add_f32 v[42:43], v[42:43], v[106:107]
	v_pk_add_f32 v[44:45], v[44:45], v[108:109]
	v_pk_add_f32 v[46:47], v[46:47], v[110:111]
	global_load_dwordx4 v[48:51], v152, s[18:19]
	global_load_dwordx4 v[52:55], v152, s[18:19] offset:1024
	global_load_dwordx4 v[56:59], v152, s[18:19] offset:2048
	global_load_dwordx4 v[60:63], v152, s[18:19] offset:3072
	s_add_u32 s18, s18, 0x200000
	s_addc_u32 s19, s19, 0
	global_load_dwordx4 v[64:67], v152, s[18:19]
	global_load_dwordx4 v[68:71], v152, s[18:19] offset:1024
	global_load_dwordx4 v[72:75], v152, s[18:19] offset:2048
	global_load_dwordx4 v[76:79], v152, s[18:19] offset:3072
	s_add_u32 s18, s18, 0x200000
	s_addc_u32 s19, s19, 0
	global_load_dwordx4 v[80:83], v152, s[18:19]
	global_load_dwordx4 v[84:87], v152, s[18:19] offset:1024
	global_load_dwordx4 v[88:91], v152, s[18:19] offset:2048
	global_load_dwordx4 v[92:95], v152, s[18:19] offset:3072
	s_add_u32 s18, s18, 0x200000
	s_addc_u32 s19, s19, 0
	global_load_dwordx4 v[96:99], v152, s[18:19]
	global_load_dwordx4 v[100:103], v152, s[18:19] offset:1024
	global_load_dwordx4 v[104:107], v152, s[18:19] offset:2048
	global_load_dwordx4 v[108:111], v152, s[18:19] offset:3072
	s_add_u32 s18, s18, 0x200000
	s_addc_u32 s19, s19, 0
	s_waitcnt vmcnt(0)
; __device__ __forceinline__ unsigned pk2(float lo, float hi) { f32x2 v = {lo, hi}; bf16x2_t b = __builtin_convertvector(v, bf16x2_t); return __builtin_bit_cast(unsigned, b); }
; __device__ __forceinline__ void sample_combine(const float* XinS  , float* X, const float* slab, int S, bf16_t* XB, float* rss, int gw, int NGW, int lane) {
;     for (int r = gw; r < TS; r += NGW) { const size_t row = (size_t)TP + r; float ss = 0.f;
; #pragma unroll
;         for (int j = 0; j < 4; ++j) { const int c = 4 * lane + 256 * j; f32x4 v = *(const f32x4*)(XinS + (size_t)r * DM + c);
;             for (int s = 0; s < S; ++s) v += *(const f32x4*)(slab + ((size_t)s * TS + r) * DM + c);
;             *(f32x4*)(X + row * DM + c) = v; ss += (v[0] * v[0] + v[1] * v[1]) + (v[2] * v[2] + v[3] * v[3]);
;             if (XB) { u32x2 w; w.x = pk2(v[0], v[1]); w.y = pk2(v[2], v[3]); *(u32x2*)(XB + row * DM + c) = w; } }
; #pragma unroll
;         for (int ofs = 1; ofs < 64; ofs <<= 1) ss += __shfl_xor(ss, ofs);
;         if (rss && lane == 0) rss[row] = ss; }
	v_pk_add_f32 v[32:33], v[32:33], v[48:49]
	v_pk_add_f32 v[34:35], v[34:35], v[50:51]
	v_pk_add_f32 v[36:37], v[36:37], v[52:53]
	v_pk_add_f32 v[38:39], v[38:39], v[54:55]
	v_pk_add_f32 v[40:41], v[40:41], v[56:57]
	v_pk_add_f32 v[42:43], v[42:43], v[58:59]
	v_pk_add_f32 v[44:45], v[44:45], v[60:61]
	v_pk_add_f32 v[46:47], v[46:47], v[62:63]
	v_pk_add_f32 v[32:33], v[32:33], v[64:65]
	v_pk_add_f32 v[34:35], v[34:35], v[66:67]
	v_pk_add_f32 v[36:37], v[36:37], v[68:69]
	v_pk_add_f32 v[38:39], v[38:39], v[70:71]
	v_pk_add_f32 v[40:41], v[40:41], v[72:73]
	v_pk_add_f32 v[42:43], v[42:43], v[74:75]
	v_pk_add_f32 v[44:45], v[44:45], v[76:77]
	v_pk_add_f32 v[46:47], v[46:47], v[78:79]
	v_pk_add_f32 v[32:33], v[32:33], v[80:81]
	v_pk_add_f32 v[34:35], v[34:35], v[82:83]
	v_pk_add_f32 v[36:37], v[36:37], v[84:85]
	v_pk_add_f32 v[38:39], v[38:39], v[86:87]
	v_pk_add_f32 v[40:41], v[40:41], v[88:89]
	v_pk_add_f32 v[42:43], v[42:43], v[90:91]
	v_pk_add_f32 v[44:45], v[44:45], v[92:93]
	v_pk_add_f32 v[46:47], v[46:47], v[94:95]
	v_pk_add_f32 v[32:33], v[32:33], v[96:97]
	v_pk_add_f32 v[34:35], v[34:35], v[98:99]
	v_pk_add_f32 v[36:37], v[36:37], v[100:101]
	v_pk_add_f32 v[38:39], v[38:39], v[102:103]
	v_pk_add_f32 v[40:41], v[40:41], v[104:105]
	v_pk_add_f32 v[42:43], v[42:43], v[106:107]
	v_pk_add_f32 v[44:45], v[44:45], v[108:109]
	v_pk_add_f32 v[46:47], v[46:47], v[110:111]
	s_add_u32 s18, s22, 0x4000000
	s_addc_u32 s19, s23, 0
	s_mov_b32 s11, 0x5400000
	v_lshl_add_u64 v[6:7], s[2:3], 0, v[0:1]
	v_add_co_u32_e32 v6, vcc, s11, v6
	s_nop 1
	v_addc_co_u32_e32 v7, vcc, 0, v7, vcc
	global_store_dwordx4 v152, v[32:35], s[18:19]
	v_mul_f32_e32 v30, v33, v33
	v_mul_f32_e32 v27, v35, v35
	v_fmac_f32_e32 v30, v32, v32
	v_fmac_f32_e32 v27, v34, v34
	v_cvt_pk_bf16_f32 v22, v32, v33
	v_cvt_pk_bf16_f32 v23, v34, v35
	v_add_f32_e32 v30, v30, v27
	global_store_dwordx2 v[6:7], v[22:23], off
	global_store_dwordx4 v152, v[36:39], s[18:19] offset:1024
	v_mul_f32_e32 v26, v37, v37
	v_mul_f32_e32 v27, v39, v39
	v_fmac_f32_e32 v26, v36, v36
	v_fmac_f32_e32 v27, v38, v38
	v_cvt_pk_bf16_f32 v24, v36, v37
	v_cvt_pk_bf16_f32 v25, v38, v39
	v_add_f32_e32 v26, v26, v27
	global_store_dwordx2 v[6:7], v[24:25], off offset:512
	v_add_f32_e32 v30, v30, v26
	global_store_dwordx4 v152, v[40:43], s[18:19] offset:2048
	v_mul_f32_e32 v26, v41, v41
	v_mul_f32_e32 v27, v43, v43
	v_fmac_f32_e32 v26, v40, v40
	v_fmac_f32_e32 v27, v42, v42
	v_cvt_pk_bf16_f32 v22, v40, v41
	v_cvt_pk_bf16_f32 v23, v42, v43
	v_add_f32_e32 v26, v26, v27
	global_store_dwordx2 v[6:7], v[22:23], off offset:1024
	v_add_f32_e32 v30, v30, v26
	global_store_dwordx4 v152, v[44:47], s[18:19] offset:3072
	v_mul_f32_e32 v26, v45, v45
	v_mul_f32_e32 v27, v47, v47
	v_fmac_f32_e32 v26, v44, v44
	v_fmac_f32_e32 v27, v46, v46
	v_cvt_pk_bf16_f32 v24, v44, v45
	v_cvt_pk_bf16_f32 v25, v46, v47
	v_add_f32_e32 v26, v26, v27
	global_store_dwordx2 v[6:7], v[24:25], off offset:1536
	v_add_f32_e32 v30, v30, v26
	v_mov_b32_e32 v4, v30
	ds_bpermute_b32 v2, v16, v4
	s_waitcnt lgkmcnt(0)
	v_add_f32_e32 v2, v4, v2
	ds_bpermute_b32 v3, v17, v2
	s_waitcnt lgkmcnt(0)
	v_add_f32_e32 v2, v2, v3
	ds_bpermute_b32 v3, v18, v2
	s_waitcnt lgkmcnt(0)
	v_add_f32_e32 v2, v2, v3
	ds_bpermute_b32 v3, v19, v2
	s_waitcnt lgkmcnt(0)
	v_add_f32_e32 v2, v2, v3
	ds_bpermute_b32 v3, v20, v2
	s_waitcnt lgkmcnt(0)
	v_add_f32_e32 v2, v2, v3
	ds_bpermute_b32 v3, v21, v2
	s_and_saveexec_b64 s[28:29], s[38:39]
	s_cbranch_execz .LBB0_655
	s_add_u32 s18, s2, s4
	s_addc_u32 s19, s3, s10
	s_waitcnt lgkmcnt(0)
	v_add_f32_e32 v2, v2, v3
	global_store_dword v153, v2, s[18:19]
	s_branch .LBB0_655
